# SwiGLU and gate epilogues: lane-pair exchange (v_permlane16_swap) gives 16-byte stores / T loads
# speedup vs baseline: 1.0477x; 1.0067x over previous
; __device__ __forceinline__ unsigned cvt_pk_bf16(float lo, float hi) { unsigned r; asm volatile("v_cvt_pk_bf16_f32 %0, %1, %2" : "=v"(r) : "v"(lo), "v"(hi)); return r; }
; __device__ __forceinline__ float sigm_f(float x) { return __builtin_amdgcn_rcpf(1.0f + __expf(-x)); }
;     __device__ __forceinline__ void operator()(const f32x4 (&acc)[2][2][4][2], const Unit& u, int wr, int wc, int fr, int fq) const {
;         const int row0 = u.pm * BM + wr * 64 + fr, col0 = u.pn * 128 + wc * 16 + 4 * fq;
; #pragma unroll
;         for (int ai = 0; ai < 2; ++ai)
; #pragma unroll
;             for (int m = 0; m < 4; ++m) { bf16_t* rowp = ACT + (size_t)(row0 + ai * HALF + m * 16) * 2816 + col0;
; #pragma unroll
;                 for (int bj = 0; bj < 2; ++bj) { const f32x4 g = acc[ai][bj][m][0], uu = acc[ai][bj][m][1];
;                     u32x2 w; w.x = cvt_pk_bf16(g[0] * sigm_f(g[0]) * uu[0], g[1] * sigm_f(g[1]) * uu[1]); w.y = cvt_pk_bf16(g[2] * sigm_f(g[2]) * uu[2], g[3] * sigm_f(g[3]) * uu[3]);
;                     *(u32x2*)(rowp + bj * 64) = w; } }
.LBB0_647:
	v_lshl_add_u32 v144, s81, 8, v3
	v_ashrrev_i32_e32 v145, 31, v144
	s_cmp_lt_i32 s16, 2
	s_mov_b64 s[10:11], -1
	s_cbranch_scc1 .LBB0_653
	s_cmp_gt_i32 s16, 2
	s_cbranch_scc0 .LBB0_650
	v_lshl_or_b32 v148, s78, 7, v165
	v_ashrrev_i32_e32 v149, 31, v148
	v_mov_b64_e32 v[146:147], s[42:43]
	v_mad_i64_i32 v[150:151], s[10:11], v144, s89, v[146:147]
	v_lshlrev_b64 v[148:149], 1, v[148:149]
	v_lshl_add_u64 v[146:147], v[150:151], 0, v[148:149]
	v_mbcnt_lo_u32_b32 v160, -1, 0
	v_mbcnt_hi_u32_b32 v160, -1, v160
	v_and_b32_e32 v160, 16, v160
	v_lshlrev_b32_e32 v161, 3, v160
	v_lshrrev_b32_e32 v160, 1, v160
	v_sub_u32_e32 v160, v161, v160
	v_mov_b32_e32 v161, 0
	v_lshl_add_u64 v[146:147], v[146:147], 0, v[160:161]
	v_mul_f32_e32 v150, 0xbfb8aa3b, v128
	v_mul_f32_e32 v151, 0xbfb8aa3b, v129
	v_mul_f32_e32 v152, 0xbfb8aa3b, v130
	v_mul_f32_e32 v153, 0xbfb8aa3b, v131
	v_mul_f32_e32 v154, 0xbfb8aa3b, v120
	v_mul_f32_e32 v155, 0xbfb8aa3b, v121
	v_mul_f32_e32 v156, 0xbfb8aa3b, v122
	v_mul_f32_e32 v157, 0xbfb8aa3b, v123
	v_exp_f32_e32 v150, v150
	v_exp_f32_e32 v151, v151
	v_exp_f32_e32 v152, v152
	v_exp_f32_e32 v153, v153
	v_exp_f32_e32 v154, v154
	v_exp_f32_e32 v155, v155
	v_exp_f32_e32 v156, v156
	v_exp_f32_e32 v157, v157
	v_add_f32_e32 v150, 1.0, v150
	v_add_f32_e32 v151, 1.0, v151
	v_add_f32_e32 v152, 1.0, v152
	v_add_f32_e32 v153, 1.0, v153
	v_add_f32_e32 v154, 1.0, v154
	v_add_f32_e32 v155, 1.0, v155
	v_add_f32_e32 v156, 1.0, v156
	v_add_f32_e32 v157, 1.0, v157
	v_rcp_f32_e32 v150, v150
	v_rcp_f32_e32 v151, v151
	v_rcp_f32_e32 v152, v152
	v_rcp_f32_e32 v153, v153
	v_rcp_f32_e32 v154, v154
	v_rcp_f32_e32 v155, v155
	v_rcp_f32_e32 v156, v156
	v_rcp_f32_e32 v157, v157
	v_mul_f32_e32 v150, v128, v150
	v_mul_f32_e32 v151, v129, v151
	v_mul_f32_e32 v152, v130, v152
	v_mul_f32_e32 v153, v131, v153
	v_mul_f32_e32 v154, v120, v154
	v_mul_f32_e32 v155, v121, v155
	v_mul_f32_e32 v156, v122, v156
	v_mul_f32_e32 v157, v123, v157
	v_mul_f32_e32 v150, v124, v150
	v_mul_f32_e32 v151, v125, v151
	v_mul_f32_e32 v152, v126, v152
	v_mul_f32_e32 v153, v127, v153
	v_mul_f32_e32 v154, v116, v154
	v_mul_f32_e32 v155, v117, v155
	v_mul_f32_e32 v156, v118, v156
	v_mul_f32_e32 v157, v119, v157
	v_cvt_pk_bf16_f32 v158, v150, v151
	v_cvt_pk_bf16_f32 v159, v152, v153
	v_cvt_pk_bf16_f32 v160, v154, v155
	v_cvt_pk_bf16_f32 v161, v156, v157
	s_nop 1
	v_permlane16_swap_b32_e32 v158, v160
	v_permlane16_swap_b32_e32 v159, v161
	s_nop 0
	global_store_dwordx4 v[146:147], v[158:161], off
	s_mov_b64 s[10:11], 0x16000
	v_lshl_add_u64 v[148:149], v[146:147], 0, s[10:11]
	v_mul_f32_e32 v150, 0xbfb8aa3b, v112
	v_mul_f32_e32 v151, 0xbfb8aa3b, v113
	v_mul_f32_e32 v152, 0xbfb8aa3b, v114
	v_mul_f32_e32 v153, 0xbfb8aa3b, v115
	v_mul_f32_e32 v154, 0xbfb8aa3b, v104
	v_mul_f32_e32 v155, 0xbfb8aa3b, v105
	v_mul_f32_e32 v156, 0xbfb8aa3b, v106
	v_mul_f32_e32 v157, 0xbfb8aa3b, v107
	v_exp_f32_e32 v150, v150
	v_exp_f32_e32 v151, v151
	v_exp_f32_e32 v152, v152
	v_exp_f32_e32 v153, v153
	v_exp_f32_e32 v154, v154
	v_exp_f32_e32 v155, v155
	v_exp_f32_e32 v156, v156
	v_exp_f32_e32 v157, v157
	v_add_f32_e32 v150, 1.0, v150
	v_add_f32_e32 v151, 1.0, v151
	v_add_f32_e32 v152, 1.0, v152
	v_add_f32_e32 v153, 1.0, v153
	v_add_f32_e32 v154, 1.0, v154
	v_add_f32_e32 v155, 1.0, v155
	v_add_f32_e32 v156, 1.0, v156
	v_add_f32_e32 v157, 1.0, v157
	v_rcp_f32_e32 v150, v150
	v_rcp_f32_e32 v151, v151
	v_rcp_f32_e32 v152, v152
	v_rcp_f32_e32 v153, v153
	v_rcp_f32_e32 v154, v154
	v_rcp_f32_e32 v155, v155
	v_rcp_f32_e32 v156, v156
	v_rcp_f32_e32 v157, v157
	v_mul_f32_e32 v150, v112, v150
	v_mul_f32_e32 v151, v113, v151
	v_mul_f32_e32 v152, v114, v152
	v_mul_f32_e32 v153, v115, v153
	v_mul_f32_e32 v154, v104, v154
	v_mul_f32_e32 v155, v105, v155
	v_mul_f32_e32 v156, v106, v156
	v_mul_f32_e32 v157, v107, v157
	v_mul_f32_e32 v150, v108, v150
	v_mul_f32_e32 v151, v109, v151
	v_mul_f32_e32 v152, v110, v152
	v_mul_f32_e32 v153, v111, v153
	v_mul_f32_e32 v154, v100, v154
	v_mul_f32_e32 v155, v101, v155
	v_mul_f32_e32 v156, v102, v156
	v_mul_f32_e32 v157, v103, v157
	v_cvt_pk_bf16_f32 v158, v150, v151
	v_cvt_pk_bf16_f32 v159, v152, v153
	v_cvt_pk_bf16_f32 v160, v154, v155
	v_cvt_pk_bf16_f32 v161, v156, v157
	s_nop 1
	v_permlane16_swap_b32_e32 v158, v160
	v_permlane16_swap_b32_e32 v159, v161
	s_nop 0
	global_store_dwordx4 v[148:149], v[158:161], off
	s_mov_b64 s[10:11], 0x2c000
	v_lshl_add_u64 v[148:149], v[146:147], 0, s[10:11]
	v_mul_f32_e32 v150, 0xbfb8aa3b, v96
	v_mul_f32_e32 v151, 0xbfb8aa3b, v97
	v_mul_f32_e32 v152, 0xbfb8aa3b, v98
	v_mul_f32_e32 v153, 0xbfb8aa3b, v99
	v_mul_f32_e32 v154, 0xbfb8aa3b, v88
	v_mul_f32_e32 v155, 0xbfb8aa3b, v89
	v_mul_f32_e32 v156, 0xbfb8aa3b, v90
	v_mul_f32_e32 v157, 0xbfb8aa3b, v91
	v_exp_f32_e32 v150, v150
	v_exp_f32_e32 v151, v151
	v_exp_f32_e32 v152, v152
	v_exp_f32_e32 v153, v153
	v_exp_f32_e32 v154, v154
	v_exp_f32_e32 v155, v155
	v_exp_f32_e32 v156, v156
	v_exp_f32_e32 v157, v157
	v_add_f32_e32 v150, 1.0, v150
	v_add_f32_e32 v151, 1.0, v151
	v_add_f32_e32 v152, 1.0, v152
	v_add_f32_e32 v153, 1.0, v153
	v_add_f32_e32 v154, 1.0, v154
	v_add_f32_e32 v155, 1.0, v155
	v_add_f32_e32 v156, 1.0, v156
	v_add_f32_e32 v157, 1.0, v157
	v_rcp_f32_e32 v150, v150
	v_rcp_f32_e32 v151, v151
	v_rcp_f32_e32 v152, v152
	v_rcp_f32_e32 v153, v153
	v_rcp_f32_e32 v154, v154
	v_rcp_f32_e32 v155, v155
	v_rcp_f32_e32 v156, v156
	v_rcp_f32_e32 v157, v157
	v_mul_f32_e32 v150, v96, v150
	v_mul_f32_e32 v151, v97, v151
	v_mul_f32_e32 v152, v98, v152
	v_mul_f32_e32 v153, v99, v153
	v_mul_f32_e32 v154, v88, v154
	v_mul_f32_e32 v155, v89, v155
	v_mul_f32_e32 v156, v90, v156
	v_mul_f32_e32 v157, v91, v157
; __device__ __forceinline__ unsigned cvt_pk_bf16(float lo, float hi) { unsigned r; asm volatile("v_cvt_pk_bf16_f32 %0, %1, %2" : "=v"(r) : "v"(lo), "v"(hi)); return r; }
; __device__ __forceinline__ float sigm_f(float x) { return __builtin_amdgcn_rcpf(1.0f + __expf(-x)); }
;     __device__ __forceinline__ void operator()(const f32x4 (&acc)[2][2][4][2], const Unit& u, int wr, int wc, int fr, int fq) const {
;     ...
;         for (int ai = 0; ai < 2; ++ai)
; #pragma unroll
;             for (int m = 0; m < 4; ++m) { bf16_t* rowp = ACT + (size_t)(row0 + ai * HALF + m * 16) * 2816 + col0;
; #pragma unroll
;                 for (int bj = 0; bj < 2; ++bj) { const f32x4 g = acc[ai][bj][m][0], uu = acc[ai][bj][m][1];
;                     u32x2 w; w.x = cvt_pk_bf16(g[0] * sigm_f(g[0]) * uu[0], g[1] * sigm_f(g[1]) * uu[1]); w.y = cvt_pk_bf16(g[2] * sigm_f(g[2]) * uu[2], g[3] * sigm_f(g[3]) * uu[3]);
;                     *(u32x2*)(rowp + bj * 64) = w; } }
	v_mul_f32_e32 v150, v92, v150
	v_mul_f32_e32 v151, v93, v151
	v_mul_f32_e32 v152, v94, v152
	v_mul_f32_e32 v153, v95, v153
	v_mul_f32_e32 v154, v84, v154
	v_mul_f32_e32 v155, v85, v155
	v_mul_f32_e32 v156, v86, v156
	v_mul_f32_e32 v157, v87, v157
	v_cvt_pk_bf16_f32 v158, v150, v151
	v_cvt_pk_bf16_f32 v159, v152, v153
	v_cvt_pk_bf16_f32 v160, v154, v155
	v_cvt_pk_bf16_f32 v161, v156, v157
	s_nop 1
	v_permlane16_swap_b32_e32 v158, v160
	v_permlane16_swap_b32_e32 v159, v161
	s_nop 0
	global_store_dwordx4 v[148:149], v[158:161], off
	s_mov_b64 s[10:11], 0x42000
	v_lshl_add_u64 v[148:149], v[146:147], 0, s[10:11]
	v_mul_f32_e32 v150, 0xbfb8aa3b, v80
	v_mul_f32_e32 v151, 0xbfb8aa3b, v81
	v_mul_f32_e32 v152, 0xbfb8aa3b, v82
	v_mul_f32_e32 v153, 0xbfb8aa3b, v83
	v_mul_f32_e32 v154, 0xbfb8aa3b, v72
	v_mul_f32_e32 v155, 0xbfb8aa3b, v73
	v_mul_f32_e32 v156, 0xbfb8aa3b, v74
	v_mul_f32_e32 v157, 0xbfb8aa3b, v75
	v_exp_f32_e32 v150, v150
	v_exp_f32_e32 v151, v151
	v_exp_f32_e32 v152, v152
	v_exp_f32_e32 v153, v153
	v_exp_f32_e32 v154, v154
	v_exp_f32_e32 v155, v155
	v_exp_f32_e32 v156, v156
	v_exp_f32_e32 v157, v157
	v_add_f32_e32 v150, 1.0, v150
	v_add_f32_e32 v151, 1.0, v151
	v_add_f32_e32 v152, 1.0, v152
	v_add_f32_e32 v153, 1.0, v153
	v_add_f32_e32 v154, 1.0, v154
	v_add_f32_e32 v155, 1.0, v155
	v_add_f32_e32 v156, 1.0, v156
	v_add_f32_e32 v157, 1.0, v157
	v_rcp_f32_e32 v150, v150
	v_rcp_f32_e32 v151, v151
	v_rcp_f32_e32 v152, v152
	v_rcp_f32_e32 v153, v153
	v_rcp_f32_e32 v154, v154
	v_rcp_f32_e32 v155, v155
	v_rcp_f32_e32 v156, v156
	v_rcp_f32_e32 v157, v157
	v_mul_f32_e32 v150, v80, v150
	v_mul_f32_e32 v151, v81, v151
	v_mul_f32_e32 v152, v82, v152
	v_mul_f32_e32 v153, v83, v153
	v_mul_f32_e32 v154, v72, v154
	v_mul_f32_e32 v155, v73, v155
	v_mul_f32_e32 v156, v74, v156
	v_mul_f32_e32 v157, v75, v157
	v_mul_f32_e32 v150, v76, v150
	v_mul_f32_e32 v151, v77, v151
	v_mul_f32_e32 v152, v78, v152
	v_mul_f32_e32 v153, v79, v153
	v_mul_f32_e32 v154, v68, v154
	v_mul_f32_e32 v155, v69, v155
	v_mul_f32_e32 v156, v70, v156
	v_mul_f32_e32 v157, v71, v157
	v_cvt_pk_bf16_f32 v158, v150, v151
	v_cvt_pk_bf16_f32 v159, v152, v153
	v_cvt_pk_bf16_f32 v160, v154, v155
	v_cvt_pk_bf16_f32 v161, v156, v157
	s_nop 1
	v_permlane16_swap_b32_e32 v158, v160
	v_permlane16_swap_b32_e32 v159, v161
	s_nop 0
	global_store_dwordx4 v[148:149], v[158:161], off
	s_mov_b64 s[10:11], 0xb0000
	v_lshl_add_u64 v[148:149], v[146:147], 0, s[10:11]
	v_mul_f32_e32 v150, 0xbfb8aa3b, v64
	v_mul_f32_e32 v151, 0xbfb8aa3b, v65
	v_mul_f32_e32 v152, 0xbfb8aa3b, v66
	v_mul_f32_e32 v153, 0xbfb8aa3b, v67
	v_mul_f32_e32 v154, 0xbfb8aa3b, v56
	v_mul_f32_e32 v155, 0xbfb8aa3b, v57
	v_mul_f32_e32 v156, 0xbfb8aa3b, v58
	v_mul_f32_e32 v157, 0xbfb8aa3b, v59
	v_exp_f32_e32 v150, v150
	v_exp_f32_e32 v151, v151
	v_exp_f32_e32 v152, v152
	v_exp_f32_e32 v153, v153
	v_exp_f32_e32 v154, v154
	v_exp_f32_e32 v155, v155
	v_exp_f32_e32 v156, v156
	v_exp_f32_e32 v157, v157
	v_add_f32_e32 v150, 1.0, v150
	v_add_f32_e32 v151, 1.0, v151
	v_add_f32_e32 v152, 1.0, v152
	v_add_f32_e32 v153, 1.0, v153
	v_add_f32_e32 v154, 1.0, v154
	v_add_f32_e32 v155, 1.0, v155
	v_add_f32_e32 v156, 1.0, v156
	v_add_f32_e32 v157, 1.0, v157
	v_rcp_f32_e32 v150, v150
	v_rcp_f32_e32 v151, v151
	v_rcp_f32_e32 v152, v152
	v_rcp_f32_e32 v153, v153
	v_rcp_f32_e32 v154, v154
	v_rcp_f32_e32 v155, v155
	v_rcp_f32_e32 v156, v156
	v_rcp_f32_e32 v157, v157
	v_mul_f32_e32 v150, v64, v150
	v_mul_f32_e32 v151, v65, v151
	v_mul_f32_e32 v152, v66, v152
	v_mul_f32_e32 v153, v67, v153
	v_mul_f32_e32 v154, v56, v154
	v_mul_f32_e32 v155, v57, v155
	v_mul_f32_e32 v156, v58, v156
	v_mul_f32_e32 v157, v59, v157
	v_mul_f32_e32 v150, v60, v150
	v_mul_f32_e32 v151, v61, v151
	v_mul_f32_e32 v152, v62, v152
	v_mul_f32_e32 v153, v63, v153
	v_mul_f32_e32 v154, v52, v154
	v_mul_f32_e32 v155, v53, v155
	v_mul_f32_e32 v156, v54, v156
	v_mul_f32_e32 v157, v55, v157
	v_cvt_pk_bf16_f32 v158, v150, v151
	v_cvt_pk_bf16_f32 v159, v152, v153
	v_cvt_pk_bf16_f32 v160, v154, v155
	v_cvt_pk_bf16_f32 v161, v156, v157
	s_nop 1
	v_permlane16_swap_b32_e32 v158, v160
	v_permlane16_swap_b32_e32 v159, v161
	s_nop 0
	global_store_dwordx4 v[148:149], v[158:161], off
	s_mov_b64 s[10:11], 0xc6000
	v_lshl_add_u64 v[148:149], v[146:147], 0, s[10:11]
	v_mul_f32_e32 v150, 0xbfb8aa3b, v48
	v_mul_f32_e32 v151, 0xbfb8aa3b, v49
	v_mul_f32_e32 v152, 0xbfb8aa3b, v50
	v_mul_f32_e32 v153, 0xbfb8aa3b, v51
	v_mul_f32_e32 v154, 0xbfb8aa3b, v40
	v_mul_f32_e32 v155, 0xbfb8aa3b, v41
	v_mul_f32_e32 v156, 0xbfb8aa3b, v42
	v_mul_f32_e32 v157, 0xbfb8aa3b, v43
	v_exp_f32_e32 v150, v150
	v_exp_f32_e32 v151, v151
	v_exp_f32_e32 v152, v152
	v_exp_f32_e32 v153, v153
	v_exp_f32_e32 v154, v154
	v_exp_f32_e32 v155, v155
	v_exp_f32_e32 v156, v156
	v_exp_f32_e32 v157, v157
	v_add_f32_e32 v150, 1.0, v150
	v_add_f32_e32 v151, 1.0, v151
; __device__ __forceinline__ unsigned cvt_pk_bf16(float lo, float hi) { unsigned r; asm volatile("v_cvt_pk_bf16_f32 %0, %1, %2" : "=v"(r) : "v"(lo), "v"(hi)); return r; }
; __device__ __forceinline__ float sigm_f(float x) { return __builtin_amdgcn_rcpf(1.0f + __expf(-x)); }
;     __device__ __forceinline__ void operator()(const f32x4 (&acc)[2][2][4][2], const Unit& u, int wr, int wc, int fr, int fq) const {
;     ...
;         for (int ai = 0; ai < 2; ++ai)
; #pragma unroll
;             for (int m = 0; m < 4; ++m) { bf16_t* rowp = ACT + (size_t)(row0 + ai * HALF + m * 16) * 2816 + col0;
; #pragma unroll
;                 for (int bj = 0; bj < 2; ++bj) { const f32x4 g = acc[ai][bj][m][0], uu = acc[ai][bj][m][1];
;                     u32x2 w; w.x = cvt_pk_bf16(g[0] * sigm_f(g[0]) * uu[0], g[1] * sigm_f(g[1]) * uu[1]); w.y = cvt_pk_bf16(g[2] * sigm_f(g[2]) * uu[2], g[3] * sigm_f(g[3]) * uu[3]);
;                     *(u32x2*)(rowp + bj * 64) = w; } }
	v_add_f32_e32 v152, 1.0, v152
	v_add_f32_e32 v153, 1.0, v153
	v_add_f32_e32 v154, 1.0, v154
	v_add_f32_e32 v155, 1.0, v155
	v_add_f32_e32 v156, 1.0, v156
	v_add_f32_e32 v157, 1.0, v157
	v_rcp_f32_e32 v150, v150
	v_rcp_f32_e32 v151, v151
	v_rcp_f32_e32 v152, v152
	v_rcp_f32_e32 v153, v153
	v_rcp_f32_e32 v154, v154
	v_rcp_f32_e32 v155, v155
	v_rcp_f32_e32 v156, v156
	v_rcp_f32_e32 v157, v157
	v_mul_f32_e32 v150, v48, v150
	v_mul_f32_e32 v151, v49, v151
	v_mul_f32_e32 v152, v50, v152
	v_mul_f32_e32 v153, v51, v153
	v_mul_f32_e32 v154, v40, v154
	v_mul_f32_e32 v155, v41, v155
	v_mul_f32_e32 v156, v42, v156
	v_mul_f32_e32 v157, v43, v157
	v_mul_f32_e32 v150, v44, v150
	v_mul_f32_e32 v151, v45, v151
	v_mul_f32_e32 v152, v46, v152
	v_mul_f32_e32 v153, v47, v153
	v_mul_f32_e32 v154, v36, v154
	v_mul_f32_e32 v155, v37, v155
	v_mul_f32_e32 v156, v38, v156
	v_mul_f32_e32 v157, v39, v157
	v_cvt_pk_bf16_f32 v158, v150, v151
	v_cvt_pk_bf16_f32 v159, v152, v153
	v_cvt_pk_bf16_f32 v160, v154, v155
	v_cvt_pk_bf16_f32 v161, v156, v157
	s_nop 1
	v_permlane16_swap_b32_e32 v158, v160
	v_permlane16_swap_b32_e32 v159, v161
	s_nop 0
	global_store_dwordx4 v[148:149], v[158:161], off
	s_mov_b64 s[10:11], 0xdc000
	v_lshl_add_u64 v[148:149], v[146:147], 0, s[10:11]
	v_mul_f32_e32 v150, 0xbfb8aa3b, v32
	v_mul_f32_e32 v151, 0xbfb8aa3b, v33
	v_mul_f32_e32 v152, 0xbfb8aa3b, v34
	v_mul_f32_e32 v153, 0xbfb8aa3b, v35
	v_mul_f32_e32 v154, 0xbfb8aa3b, v24
	v_mul_f32_e32 v155, 0xbfb8aa3b, v25
	v_mul_f32_e32 v156, 0xbfb8aa3b, v26
	v_mul_f32_e32 v157, 0xbfb8aa3b, v27
	v_exp_f32_e32 v150, v150
	v_exp_f32_e32 v151, v151
	v_exp_f32_e32 v152, v152
	v_exp_f32_e32 v153, v153
	v_exp_f32_e32 v154, v154
	v_exp_f32_e32 v155, v155
	v_exp_f32_e32 v156, v156
	v_exp_f32_e32 v157, v157
	v_add_f32_e32 v150, 1.0, v150
	v_add_f32_e32 v151, 1.0, v151
	v_add_f32_e32 v152, 1.0, v152
	v_add_f32_e32 v153, 1.0, v153
	v_add_f32_e32 v154, 1.0, v154
	v_add_f32_e32 v155, 1.0, v155
	v_add_f32_e32 v156, 1.0, v156
	v_add_f32_e32 v157, 1.0, v157
	v_rcp_f32_e32 v150, v150
	v_rcp_f32_e32 v151, v151
	v_rcp_f32_e32 v152, v152
	v_rcp_f32_e32 v153, v153
	v_rcp_f32_e32 v154, v154
	v_rcp_f32_e32 v155, v155
	v_rcp_f32_e32 v156, v156
	v_rcp_f32_e32 v157, v157
	v_mul_f32_e32 v150, v32, v150
	v_mul_f32_e32 v151, v33, v151
	v_mul_f32_e32 v152, v34, v152
	v_mul_f32_e32 v153, v35, v153
	v_mul_f32_e32 v154, v24, v154
	v_mul_f32_e32 v155, v25, v155
	v_mul_f32_e32 v156, v26, v156
	v_mul_f32_e32 v157, v27, v157
	v_mul_f32_e32 v150, v28, v150
	v_mul_f32_e32 v151, v29, v151
	v_mul_f32_e32 v152, v30, v152
	v_mul_f32_e32 v153, v31, v153
	v_mul_f32_e32 v154, v20, v154
	v_mul_f32_e32 v155, v21, v155
	v_mul_f32_e32 v156, v22, v156
	v_mul_f32_e32 v157, v23, v157
	v_cvt_pk_bf16_f32 v158, v150, v151
	v_cvt_pk_bf16_f32 v159, v152, v153
	v_cvt_pk_bf16_f32 v160, v154, v155
	v_cvt_pk_bf16_f32 v161, v156, v157
	s_nop 1
	v_permlane16_swap_b32_e32 v158, v160
	v_permlane16_swap_b32_e32 v159, v161
	s_nop 0
	global_store_dwordx4 v[148:149], v[158:161], off
	s_mov_b64 s[10:11], 0xf2000
	v_lshl_add_u64 v[148:149], v[146:147], 0, s[10:11]
	v_mul_f32_e32 v150, 0xbfb8aa3b, v16
	v_mul_f32_e32 v151, 0xbfb8aa3b, v17
	v_mul_f32_e32 v152, 0xbfb8aa3b, v18
	v_mul_f32_e32 v153, 0xbfb8aa3b, v19
	v_mul_f32_e32 v154, 0xbfb8aa3b, v8
	v_mul_f32_e32 v155, 0xbfb8aa3b, v9
	v_mul_f32_e32 v156, 0xbfb8aa3b, v10
	v_mul_f32_e32 v157, 0xbfb8aa3b, v11
	v_exp_f32_e32 v150, v150
	v_exp_f32_e32 v151, v151
	v_exp_f32_e32 v152, v152
	v_exp_f32_e32 v153, v153
	v_exp_f32_e32 v154, v154
	v_exp_f32_e32 v155, v155
	v_exp_f32_e32 v156, v156
	v_exp_f32_e32 v157, v157
	v_add_f32_e32 v150, 1.0, v150
	v_add_f32_e32 v151, 1.0, v151
	v_add_f32_e32 v152, 1.0, v152
	v_add_f32_e32 v153, 1.0, v153
	v_add_f32_e32 v154, 1.0, v154
	v_add_f32_e32 v155, 1.0, v155
	v_add_f32_e32 v156, 1.0, v156
	v_add_f32_e32 v157, 1.0, v157
	v_rcp_f32_e32 v150, v150
	v_rcp_f32_e32 v151, v151
	v_rcp_f32_e32 v152, v152
	v_rcp_f32_e32 v153, v153
	v_rcp_f32_e32 v154, v154
	v_rcp_f32_e32 v155, v155
	v_rcp_f32_e32 v156, v156
	v_rcp_f32_e32 v157, v157
	v_mul_f32_e32 v150, v16, v150
	v_mul_f32_e32 v151, v17, v151
	v_mul_f32_e32 v152, v18, v152
	v_mul_f32_e32 v153, v19, v153
	v_mul_f32_e32 v154, v8, v154
	v_mul_f32_e32 v155, v9, v155
	v_mul_f32_e32 v156, v10, v156
	v_mul_f32_e32 v157, v11, v157
	v_mul_f32_e32 v150, v12, v150
	v_mul_f32_e32 v151, v13, v151
	v_mul_f32_e32 v152, v14, v152
	v_mul_f32_e32 v153, v15, v153
	v_mul_f32_e32 v154, v4, v154
	v_mul_f32_e32 v155, v5, v155
	v_mul_f32_e32 v156, v6, v156
	v_mul_f32_e32 v157, v7, v157
	v_cvt_pk_bf16_f32 v158, v150, v151
	v_cvt_pk_bf16_f32 v159, v152, v153
	v_cvt_pk_bf16_f32 v160, v154, v155
	v_cvt_pk_bf16_f32 v161, v156, v157
	s_nop 1
	v_permlane16_swap_b32_e32 v158, v160
	v_permlane16_swap_b32_e32 v159, v161
	s_nop 0
	global_store_dwordx4 v[148:149], v[158:161], off
	s_mov_b64 s[10:11], 0

; __device__ __forceinline__ float sigm_f(float x) { return __builtin_amdgcn_rcpf(1.0f + __expf(-x)); }
; __device__ __forceinline__ float ebflo(unsigned w) { return __uint_as_float(w << 16); }
; __device__ __forceinline__ float ebfhi(unsigned w) { return __uint_as_float(w & 0xffff0000u); }
;     __device__ __forceinline__ void operator()(const f32x4 (&acc)[2][2][4][2], const Unit& u, int wr, int wc, int fr, int fq) const {
;         const int row0 = u.pm * BM + wr * 64 + fr, j0 = u.pn * 64 + wc * 16 + 4 * fq;
; #pragma unroll
;         for (int ai = 0; ai < 2; ++ai)
; #pragma unroll
;             for (int m = 0; m < 4; ++m) { const size_t off = (size_t)(row0 + ai * HALF + m * 16) * 1024 + j0;
;                 const u32x2 t0 = *(const u32x2*)(T0 + off), t1 = *(const u32x2*)(T1 + off), t2 = *(const u32x2*)(T2 + off), t3 = *(const u32x2*)(T3 + off);
;                 const f32x4 g0 = acc[ai][0][m][0], g1 = acc[ai][0][m][1], g2 = acc[ai][1][m][0], g3 = acc[ai][1][m][1];
;                 const float r0 = (sigm_f(g0[0]) * ebflo(t0.x) + sigm_f(g1[0]) * ebflo(t1.x)) + (sigm_f(g2[0]) * ebflo(t2.x) + sigm_f(g3[0]) * ebflo(t3.x));
;                 const float r1 = (sigm_f(g0[1]) * ebfhi(t0.x) + sigm_f(g1[1]) * ebfhi(t1.x)) + (sigm_f(g2[1]) * ebfhi(t2.x) + sigm_f(g3[1]) * ebfhi(t3.x));
;                 const float r2 = (sigm_f(g0[2]) * ebflo(t0.y) + sigm_f(g1[2]) * ebflo(t1.y)) + (sigm_f(g2[2]) * ebflo(t2.y) + sigm_f(g3[2]) * ebflo(t3.y));
;                 const float r3 = (sigm_f(g0[3]) * ebfhi(t0.y) + sigm_f(g1[3]) * ebfhi(t1.y)) + (sigm_f(g2[3]) * ebfhi(t2.y) + sigm_f(g3[3]) * ebfhi(t3.y));
.LBB0_656:
	s_andn2_b64 vcc, exec, s[10:11]
	s_cbranch_vccnz .LBB0_658
	v_lshl_or_b32 v148, s78, 6, v165
	v_ashrrev_i32_e32 v149, 31, v148
	v_lshlrev_b64 v[144:145], 10, v[144:145]
	v_lshl_add_u64 v[144:145], v[144:145], 0, v[148:149]
	v_lshlrev_b64 v[144:145], 1, v[144:145]
	v_mbcnt_lo_u32_b32 v146, -1, 0
	v_mbcnt_hi_u32_b32 v146, -1, v146
	v_and_b32_e32 v146, 16, v146
	v_lshlrev_b32_e32 v147, 11, v146
	v_lshrrev_b32_e32 v146, 1, v146
	v_sub_u32_e32 v146, v147, v146
	v_add_u32_e32 v146, v146, v144
	global_load_dwordx4 v[190:193], v146, s[74:75]
	global_load_dwordx4 v[194:197], v146, s[72:73]
	global_load_dwordx4 v[198:201], v146, s[84:85]
	global_load_dwordx4 v[202:205], v146, s[48:49]
	v_add_u32_e32 v147, 0x10000, v146
	global_load_dwordx4 v[206:209], v147, s[74:75]
	global_load_dwordx4 v[210:213], v147, s[72:73]
	global_load_dwordx4 v[214:217], v147, s[84:85]
	global_load_dwordx4 v[218:221], v147, s[48:49]
	v_add_u32_e32 v147, 0x40000, v146
	global_load_dwordx4 v[222:225], v147, s[74:75]
	global_load_dwordx4 v[226:229], v147, s[72:73]
	global_load_dwordx4 v[230:233], v147, s[84:85]
	global_load_dwordx4 v[234:237], v147, s[48:49]
	v_add_u32_e32 v147, 0x50000, v146
	global_load_dwordx4 v[238:241], v147, s[74:75]
	global_load_dwordx4 v[242:245], v147, s[72:73]
	global_load_dwordx4 v[152:155], v147, s[84:85]
	global_load_dwordx4 v[156:159], v147, s[48:49]
	v_mul_f32_e32 v128, 0xbfb8aa3b, v128
	v_mul_f32_e32 v129, 0xbfb8aa3b, v129
	v_mul_f32_e32 v130, 0xbfb8aa3b, v130
	v_mul_f32_e32 v131, 0xbfb8aa3b, v131
	v_mul_f32_e32 v124, 0xbfb8aa3b, v124
	v_mul_f32_e32 v125, 0xbfb8aa3b, v125
	v_mul_f32_e32 v126, 0xbfb8aa3b, v126
	v_mul_f32_e32 v127, 0xbfb8aa3b, v127
	v_mul_f32_e32 v120, 0xbfb8aa3b, v120
	v_mul_f32_e32 v121, 0xbfb8aa3b, v121
	v_mul_f32_e32 v122, 0xbfb8aa3b, v122
	v_mul_f32_e32 v123, 0xbfb8aa3b, v123
	v_mul_f32_e32 v116, 0xbfb8aa3b, v116
	v_mul_f32_e32 v117, 0xbfb8aa3b, v117
	v_mul_f32_e32 v118, 0xbfb8aa3b, v118
	v_mul_f32_e32 v119, 0xbfb8aa3b, v119
	v_mul_f32_e32 v112, 0xbfb8aa3b, v112
	v_mul_f32_e32 v113, 0xbfb8aa3b, v113
	v_mul_f32_e32 v114, 0xbfb8aa3b, v114
	v_mul_f32_e32 v115, 0xbfb8aa3b, v115
	v_mul_f32_e32 v108, 0xbfb8aa3b, v108
	v_mul_f32_e32 v109, 0xbfb8aa3b, v109
	v_mul_f32_e32 v110, 0xbfb8aa3b, v110
	v_mul_f32_e32 v111, 0xbfb8aa3b, v111
	v_mul_f32_e32 v104, 0xbfb8aa3b, v104
	v_mul_f32_e32 v105, 0xbfb8aa3b, v105
	v_mul_f32_e32 v106, 0xbfb8aa3b, v106
	v_mul_f32_e32 v107, 0xbfb8aa3b, v107
	v_mul_f32_e32 v100, 0xbfb8aa3b, v100
	v_mul_f32_e32 v101, 0xbfb8aa3b, v101
	v_mul_f32_e32 v102, 0xbfb8aa3b, v102
	v_mul_f32_e32 v103, 0xbfb8aa3b, v103
	v_exp_f32_e32 v128, v128
	v_exp_f32_e32 v129, v129
	v_exp_f32_e32 v130, v130
	v_exp_f32_e32 v131, v131
	v_exp_f32_e32 v124, v124
	v_exp_f32_e32 v125, v125
	v_exp_f32_e32 v126, v126
	v_exp_f32_e32 v127, v127
	v_exp_f32_e32 v120, v120
	v_exp_f32_e32 v121, v121
	v_exp_f32_e32 v122, v122
	v_exp_f32_e32 v123, v123
	v_exp_f32_e32 v116, v116
	v_exp_f32_e32 v117, v117
	v_exp_f32_e32 v118, v118
	v_exp_f32_e32 v119, v119
	v_exp_f32_e32 v112, v112
	v_exp_f32_e32 v113, v113
	v_exp_f32_e32 v114, v114
	v_exp_f32_e32 v115, v115
	v_exp_f32_e32 v108, v108
	v_exp_f32_e32 v109, v109
	v_exp_f32_e32 v110, v110
	v_exp_f32_e32 v111, v111
	v_exp_f32_e32 v104, v104
	v_exp_f32_e32 v105, v105
	v_exp_f32_e32 v106, v106
	v_exp_f32_e32 v107, v107
	v_exp_f32_e32 v100, v100
	v_exp_f32_e32 v101, v101
	v_exp_f32_e32 v102, v102
	v_exp_f32_e32 v103, v103
	v_add_f32_e32 v128, 1.0, v128
	v_add_f32_e32 v129, 1.0, v129
	v_add_f32_e32 v130, 1.0, v130
	v_add_f32_e32 v131, 1.0, v131
	v_add_f32_e32 v124, 1.0, v124
	v_add_f32_e32 v125, 1.0, v125
	v_add_f32_e32 v126, 1.0, v126
	v_add_f32_e32 v127, 1.0, v127
	v_add_f32_e32 v120, 1.0, v120
	v_add_f32_e32 v121, 1.0, v121
	v_add_f32_e32 v122, 1.0, v122
	v_add_f32_e32 v123, 1.0, v123
	v_add_f32_e32 v116, 1.0, v116
	v_add_f32_e32 v117, 1.0, v117
	v_add_f32_e32 v118, 1.0, v118
	v_add_f32_e32 v119, 1.0, v119
	v_add_f32_e32 v112, 1.0, v112
	v_add_f32_e32 v113, 1.0, v113
	v_add_f32_e32 v114, 1.0, v114
	v_add_f32_e32 v115, 1.0, v115
	v_add_f32_e32 v108, 1.0, v108
	v_add_f32_e32 v109, 1.0, v109
	v_add_f32_e32 v110, 1.0, v110
	v_add_f32_e32 v111, 1.0, v111
	v_add_f32_e32 v104, 1.0, v104
	v_add_f32_e32 v105, 1.0, v105
	v_add_f32_e32 v106, 1.0, v106
	v_add_f32_e32 v107, 1.0, v107
	v_add_f32_e32 v100, 1.0, v100
	v_add_f32_e32 v101, 1.0, v101
	v_add_f32_e32 v102, 1.0, v102
	v_add_f32_e32 v103, 1.0, v103
	v_rcp_f32_e32 v128, v128
	v_rcp_f32_e32 v129, v129
	v_rcp_f32_e32 v130, v130
	v_rcp_f32_e32 v131, v131
	v_rcp_f32_e32 v124, v124
	v_rcp_f32_e32 v125, v125
	v_rcp_f32_e32 v126, v126
	v_rcp_f32_e32 v127, v127
	v_rcp_f32_e32 v120, v120
	v_rcp_f32_e32 v121, v121
	v_rcp_f32_e32 v122, v122
	v_rcp_f32_e32 v123, v123
	v_rcp_f32_e32 v116, v116
	v_rcp_f32_e32 v117, v117
	v_rcp_f32_e32 v118, v118
	v_rcp_f32_e32 v119, v119
	v_rcp_f32_e32 v112, v112
	v_rcp_f32_e32 v113, v113
	v_rcp_f32_e32 v114, v114
	v_rcp_f32_e32 v115, v115
	v_rcp_f32_e32 v108, v108
	v_rcp_f32_e32 v109, v109
	v_rcp_f32_e32 v110, v110
	v_rcp_f32_e32 v111, v111
	v_rcp_f32_e32 v104, v104
	v_rcp_f32_e32 v105, v105
	v_rcp_f32_e32 v106, v106
	v_rcp_f32_e32 v107, v107
	v_rcp_f32_e32 v100, v100
	v_rcp_f32_e32 v101, v101
	v_rcp_f32_e32 v102, v102
	v_rcp_f32_e32 v103, v103
	s_nop 1
	v_permlane16_swap_b32_e32 v128, v112
	v_permlane16_swap_b32_e32 v129, v113
	v_permlane16_swap_b32_e32 v130, v114
	v_permlane16_swap_b32_e32 v131, v115
	v_permlane16_swap_b32_e32 v124, v108
	v_permlane16_swap_b32_e32 v125, v109
	v_permlane16_swap_b32_e32 v126, v110
	v_permlane16_swap_b32_e32 v127, v111
	v_permlane16_swap_b32_e32 v120, v104
	v_permlane16_swap_b32_e32 v121, v105
	v_permlane16_swap_b32_e32 v122, v106
	v_permlane16_swap_b32_e32 v123, v107
	v_permlane16_swap_b32_e32 v116, v100
	v_permlane16_swap_b32_e32 v117, v101
	v_permlane16_swap_b32_e32 v118, v102
	v_permlane16_swap_b32_e32 v119, v103
	s_waitcnt vmcnt(0)
; __device__ __forceinline__ unsigned cvt_pk_bf16(float lo, float hi) { unsigned r; asm volatile("v_cvt_pk_bf16_f32 %0, %1, %2" : "=v"(r) : "v"(lo), "v"(hi)); return r; }
; __device__ __forceinline__ float sigm_f(float x) { return __builtin_amdgcn_rcpf(1.0f + __expf(-x)); }
; __device__ __forceinline__ float ebflo(unsigned w) { return __uint_as_float(w << 16); }
; __device__ __forceinline__ float ebfhi(unsigned w) { return __uint_as_float(w & 0xffff0000u); }
;     __device__ __forceinline__ void operator()(const f32x4 (&acc)[2][2][4][2], const Unit& u, int wr, int wc, int fr, int fq) const {
;     ...
;                 const u32x2 t0 = *(const u32x2*)(T0 + off), t1 = *(const u32x2*)(T1 + off), t2 = *(const u32x2*)(T2 + off), t3 = *(const u32x2*)(T3 + off);
;                 const f32x4 g0 = acc[ai][0][m][0], g1 = acc[ai][0][m][1], g2 = acc[ai][1][m][0], g3 = acc[ai][1][m][1];
;                 const float r0 = (sigm_f(g0[0]) * ebflo(t0.x) + sigm_f(g1[0]) * ebflo(t1.x)) + (sigm_f(g2[0]) * ebflo(t2.x) + sigm_f(g3[0]) * ebflo(t3.x));
;                 const float r1 = (sigm_f(g0[1]) * ebfhi(t0.x) + sigm_f(g1[1]) * ebfhi(t1.x)) + (sigm_f(g2[1]) * ebfhi(t2.x) + sigm_f(g3[1]) * ebfhi(t3.x));
;                 const float r2 = (sigm_f(g0[2]) * ebflo(t0.y) + sigm_f(g1[2]) * ebflo(t1.y)) + (sigm_f(g2[2]) * ebflo(t2.y) + sigm_f(g3[2]) * ebflo(t3.y));
;                 const float r3 = (sigm_f(g0[3]) * ebfhi(t0.y) + sigm_f(g1[3]) * ebfhi(t1.y)) + (sigm_f(g2[3]) * ebfhi(t2.y) + sigm_f(g3[3]) * ebfhi(t3.y));
;                 u32x2 w; w.x = cvt_pk_bf16(r0, r1); w.y = cvt_pk_bf16(r2, r3);
;                 *(u32x2*)(MRG + off) = w; }
	v_lshlrev_b32_e32 v150, 16, v190
	v_lshlrev_b32_e32 v151, 16, v194
	v_lshlrev_b32_e32 v160, 16, v198
	v_lshlrev_b32_e32 v161, 16, v202
	v_mul_f32_e32 v124, v124, v151
	v_mul_f32_e32 v116, v116, v161
	v_fmac_f32_e32 v124, v128, v150
	v_fmac_f32_e32 v116, v120, v160
	v_add_f32_e32 v124, v124, v116
	v_and_b32_e32 v150, 0xffff0000, v190
	v_and_b32_e32 v151, 0xffff0000, v194
	v_and_b32_e32 v160, 0xffff0000, v198
	v_and_b32_e32 v161, 0xffff0000, v202
	v_mul_f32_e32 v125, v125, v151
	v_mul_f32_e32 v117, v117, v161
	v_fmac_f32_e32 v125, v129, v150
	v_fmac_f32_e32 v117, v121, v160
	v_add_f32_e32 v125, v125, v117
	v_lshlrev_b32_e32 v150, 16, v191
	v_lshlrev_b32_e32 v151, 16, v195
	v_lshlrev_b32_e32 v160, 16, v199
	v_lshlrev_b32_e32 v161, 16, v203
	v_mul_f32_e32 v126, v126, v151
	v_mul_f32_e32 v118, v118, v161
	v_fmac_f32_e32 v126, v130, v150
	v_fmac_f32_e32 v118, v122, v160
	v_add_f32_e32 v126, v126, v118
	v_and_b32_e32 v150, 0xffff0000, v191
	v_and_b32_e32 v151, 0xffff0000, v195
	v_and_b32_e32 v160, 0xffff0000, v199
	v_and_b32_e32 v161, 0xffff0000, v203
	v_mul_f32_e32 v127, v127, v151
	v_mul_f32_e32 v119, v119, v161
	v_fmac_f32_e32 v127, v131, v150
	v_fmac_f32_e32 v119, v123, v160
	v_add_f32_e32 v127, v127, v119
	v_lshlrev_b32_e32 v150, 16, v192
	v_lshlrev_b32_e32 v151, 16, v196
	v_lshlrev_b32_e32 v160, 16, v200
	v_lshlrev_b32_e32 v161, 16, v204
	v_mul_f32_e32 v108, v108, v151
	v_mul_f32_e32 v100, v100, v161
	v_fmac_f32_e32 v108, v112, v150
	v_fmac_f32_e32 v100, v104, v160
	v_add_f32_e32 v108, v108, v100
	v_and_b32_e32 v150, 0xffff0000, v192
	v_and_b32_e32 v151, 0xffff0000, v196
	v_and_b32_e32 v160, 0xffff0000, v200
	v_and_b32_e32 v161, 0xffff0000, v204
	v_mul_f32_e32 v109, v109, v151
	v_mul_f32_e32 v101, v101, v161
	v_fmac_f32_e32 v109, v113, v150
	v_fmac_f32_e32 v101, v105, v160
	v_add_f32_e32 v109, v109, v101
	v_lshlrev_b32_e32 v150, 16, v193
	v_lshlrev_b32_e32 v151, 16, v197
	v_lshlrev_b32_e32 v160, 16, v201
	v_lshlrev_b32_e32 v161, 16, v205
	v_mul_f32_e32 v110, v110, v151
	v_mul_f32_e32 v102, v102, v161
	v_fmac_f32_e32 v110, v114, v150
	v_fmac_f32_e32 v102, v106, v160
	v_add_f32_e32 v110, v110, v102
	v_and_b32_e32 v150, 0xffff0000, v193
	v_and_b32_e32 v151, 0xffff0000, v197
	v_and_b32_e32 v160, 0xffff0000, v201
	v_and_b32_e32 v161, 0xffff0000, v205
	v_mul_f32_e32 v111, v111, v151
	v_mul_f32_e32 v103, v103, v161
	v_fmac_f32_e32 v111, v115, v150
	v_fmac_f32_e32 v103, v107, v160
	v_add_f32_e32 v111, v111, v103
	v_cvt_pk_bf16_f32 v190, v124, v125
	v_cvt_pk_bf16_f32 v191, v126, v127
	v_cvt_pk_bf16_f32 v192, v108, v109
	v_cvt_pk_bf16_f32 v193, v110, v111
	s_nop 0
	global_store_dwordx4 v146, v[190:193], s[74:75]
	v_mul_f32_e32 v96, 0xbfb8aa3b, v96
	v_mul_f32_e32 v97, 0xbfb8aa3b, v97
	v_mul_f32_e32 v98, 0xbfb8aa3b, v98
	v_mul_f32_e32 v99, 0xbfb8aa3b, v99
	v_mul_f32_e32 v92, 0xbfb8aa3b, v92
	v_mul_f32_e32 v93, 0xbfb8aa3b, v93
	v_mul_f32_e32 v94, 0xbfb8aa3b, v94
	v_mul_f32_e32 v95, 0xbfb8aa3b, v95
	v_mul_f32_e32 v88, 0xbfb8aa3b, v88
	v_mul_f32_e32 v89, 0xbfb8aa3b, v89
	v_mul_f32_e32 v90, 0xbfb8aa3b, v90
	v_mul_f32_e32 v91, 0xbfb8aa3b, v91
	v_mul_f32_e32 v84, 0xbfb8aa3b, v84
	v_mul_f32_e32 v85, 0xbfb8aa3b, v85
	v_mul_f32_e32 v86, 0xbfb8aa3b, v86
	v_mul_f32_e32 v87, 0xbfb8aa3b, v87
	v_mul_f32_e32 v80, 0xbfb8aa3b, v80
	v_mul_f32_e32 v81, 0xbfb8aa3b, v81
	v_mul_f32_e32 v82, 0xbfb8aa3b, v82
	v_mul_f32_e32 v83, 0xbfb8aa3b, v83
	v_mul_f32_e32 v76, 0xbfb8aa3b, v76
	v_mul_f32_e32 v77, 0xbfb8aa3b, v77
	v_mul_f32_e32 v78, 0xbfb8aa3b, v78
	v_mul_f32_e32 v79, 0xbfb8aa3b, v79
	v_mul_f32_e32 v72, 0xbfb8aa3b, v72
	v_mul_f32_e32 v73, 0xbfb8aa3b, v73
	v_mul_f32_e32 v74, 0xbfb8aa3b, v74
	v_mul_f32_e32 v75, 0xbfb8aa3b, v75
	v_mul_f32_e32 v68, 0xbfb8aa3b, v68
	v_mul_f32_e32 v69, 0xbfb8aa3b, v69
	v_mul_f32_e32 v70, 0xbfb8aa3b, v70
	v_mul_f32_e32 v71, 0xbfb8aa3b, v71
	v_exp_f32_e32 v96, v96
	v_exp_f32_e32 v97, v97
	v_exp_f32_e32 v98, v98
	v_exp_f32_e32 v99, v99
	v_exp_f32_e32 v92, v92
	v_exp_f32_e32 v93, v93
	v_exp_f32_e32 v94, v94
	v_exp_f32_e32 v95, v95
	v_exp_f32_e32 v88, v88
	v_exp_f32_e32 v89, v89
	v_exp_f32_e32 v90, v90
	v_exp_f32_e32 v91, v91
	v_exp_f32_e32 v84, v84
	v_exp_f32_e32 v85, v85
	v_exp_f32_e32 v86, v86
	v_exp_f32_e32 v87, v87
	v_exp_f32_e32 v80, v80
	v_exp_f32_e32 v81, v81
	v_exp_f32_e32 v82, v82
	v_exp_f32_e32 v83, v83
	v_exp_f32_e32 v76, v76
	v_exp_f32_e32 v77, v77
	v_exp_f32_e32 v78, v78
	v_exp_f32_e32 v79, v79
	v_exp_f32_e32 v72, v72
	v_exp_f32_e32 v73, v73
	v_exp_f32_e32 v74, v74
	v_exp_f32_e32 v75, v75
	v_exp_f32_e32 v68, v68
	v_exp_f32_e32 v69, v69
	v_exp_f32_e32 v70, v70
	v_exp_f32_e32 v71, v71
	v_add_f32_e32 v96, 1.0, v96
	v_add_f32_e32 v97, 1.0, v97
	v_add_f32_e32 v98, 1.0, v98
	v_add_f32_e32 v99, 1.0, v99
	v_add_f32_e32 v92, 1.0, v92
	v_add_f32_e32 v93, 1.0, v93
	v_add_f32_e32 v94, 1.0, v94
	v_add_f32_e32 v95, 1.0, v95
	v_add_f32_e32 v88, 1.0, v88
	v_add_f32_e32 v89, 1.0, v89
	v_add_f32_e32 v90, 1.0, v90
	v_add_f32_e32 v91, 1.0, v91
	v_add_f32_e32 v84, 1.0, v84
	v_add_f32_e32 v85, 1.0, v85
	v_add_f32_e32 v86, 1.0, v86
	v_add_f32_e32 v87, 1.0, v87
	v_add_f32_e32 v80, 1.0, v80
	v_add_f32_e32 v81, 1.0, v81
	v_add_f32_e32 v82, 1.0, v82
	v_add_f32_e32 v83, 1.0, v83
	v_add_f32_e32 v76, 1.0, v76
	v_add_f32_e32 v77, 1.0, v77
	v_add_f32_e32 v78, 1.0, v78
	v_add_f32_e32 v79, 1.0, v79
	v_add_f32_e32 v72, 1.0, v72
	v_add_f32_e32 v73, 1.0, v73
	v_add_f32_e32 v74, 1.0, v74
	v_add_f32_e32 v75, 1.0, v75
	v_add_f32_e32 v68, 1.0, v68
	v_add_f32_e32 v69, 1.0, v69
	v_add_f32_e32 v70, 1.0, v70
	v_add_f32_e32 v71, 1.0, v71
	v_rcp_f32_e32 v96, v96
	v_rcp_f32_e32 v97, v97
	v_rcp_f32_e32 v98, v98
	v_rcp_f32_e32 v99, v99
	v_rcp_f32_e32 v92, v92
	v_rcp_f32_e32 v93, v93
; __device__ __forceinline__ unsigned cvt_pk_bf16(float lo, float hi) { unsigned r; asm volatile("v_cvt_pk_bf16_f32 %0, %1, %2" : "=v"(r) : "v"(lo), "v"(hi)); return r; }
; __device__ __forceinline__ float sigm_f(float x) { return __builtin_amdgcn_rcpf(1.0f + __expf(-x)); }
; __device__ __forceinline__ float ebflo(unsigned w) { return __uint_as_float(w << 16); }
; __device__ __forceinline__ float ebfhi(unsigned w) { return __uint_as_float(w & 0xffff0000u); }
;     __device__ __forceinline__ void operator()(const f32x4 (&acc)[2][2][4][2], const Unit& u, int wr, int wc, int fr, int fq) const {
;     ...
;             for (int m = 0; m < 4; ++m) { const size_t off = (size_t)(row0 + ai * HALF + m * 16) * 1024 + j0;
;                 const u32x2 t0 = *(const u32x2*)(T0 + off), t1 = *(const u32x2*)(T1 + off), t2 = *(const u32x2*)(T2 + off), t3 = *(const u32x2*)(T3 + off);
;                 const f32x4 g0 = acc[ai][0][m][0], g1 = acc[ai][0][m][1], g2 = acc[ai][1][m][0], g3 = acc[ai][1][m][1];
;                 const float r0 = (sigm_f(g0[0]) * ebflo(t0.x) + sigm_f(g1[0]) * ebflo(t1.x)) + (sigm_f(g2[0]) * ebflo(t2.x) + sigm_f(g3[0]) * ebflo(t3.x));
;                 const float r1 = (sigm_f(g0[1]) * ebfhi(t0.x) + sigm_f(g1[1]) * ebfhi(t1.x)) + (sigm_f(g2[1]) * ebfhi(t2.x) + sigm_f(g3[1]) * ebfhi(t3.x));
;                 const float r2 = (sigm_f(g0[2]) * ebflo(t0.y) + sigm_f(g1[2]) * ebflo(t1.y)) + (sigm_f(g2[2]) * ebflo(t2.y) + sigm_f(g3[2]) * ebflo(t3.y));
;                 const float r3 = (sigm_f(g0[3]) * ebfhi(t0.y) + sigm_f(g1[3]) * ebfhi(t1.y)) + (sigm_f(g2[3]) * ebfhi(t2.y) + sigm_f(g3[3]) * ebfhi(t3.y));
;                 u32x2 w; w.x = cvt_pk_bf16(r0, r1); w.y = cvt_pk_bf16(r2, r3);
;                 *(u32x2*)(MRG + off) = w; }
	v_rcp_f32_e32 v94, v94
	v_rcp_f32_e32 v95, v95
	v_rcp_f32_e32 v88, v88
	v_rcp_f32_e32 v89, v89
	v_rcp_f32_e32 v90, v90
	v_rcp_f32_e32 v91, v91
	v_rcp_f32_e32 v84, v84
	v_rcp_f32_e32 v85, v85
	v_rcp_f32_e32 v86, v86
	v_rcp_f32_e32 v87, v87
	v_rcp_f32_e32 v80, v80
	v_rcp_f32_e32 v81, v81
	v_rcp_f32_e32 v82, v82
	v_rcp_f32_e32 v83, v83
	v_rcp_f32_e32 v76, v76
	v_rcp_f32_e32 v77, v77
	v_rcp_f32_e32 v78, v78
	v_rcp_f32_e32 v79, v79
	v_rcp_f32_e32 v72, v72
	v_rcp_f32_e32 v73, v73
	v_rcp_f32_e32 v74, v74
	v_rcp_f32_e32 v75, v75
	v_rcp_f32_e32 v68, v68
	v_rcp_f32_e32 v69, v69
	v_rcp_f32_e32 v70, v70
	v_rcp_f32_e32 v71, v71
	s_nop 1
	v_permlane16_swap_b32_e32 v96, v80
	v_permlane16_swap_b32_e32 v97, v81
	v_permlane16_swap_b32_e32 v98, v82
	v_permlane16_swap_b32_e32 v99, v83
	v_permlane16_swap_b32_e32 v92, v76
	v_permlane16_swap_b32_e32 v93, v77
	v_permlane16_swap_b32_e32 v94, v78
	v_permlane16_swap_b32_e32 v95, v79
	v_permlane16_swap_b32_e32 v88, v72
	v_permlane16_swap_b32_e32 v89, v73
	v_permlane16_swap_b32_e32 v90, v74
	v_permlane16_swap_b32_e32 v91, v75
	v_permlane16_swap_b32_e32 v84, v68
	v_permlane16_swap_b32_e32 v85, v69
	v_permlane16_swap_b32_e32 v86, v70
	v_permlane16_swap_b32_e32 v87, v71
	v_lshlrev_b32_e32 v150, 16, v206
	v_lshlrev_b32_e32 v151, 16, v210
	v_lshlrev_b32_e32 v160, 16, v214
	v_lshlrev_b32_e32 v161, 16, v218
	v_mul_f32_e32 v92, v92, v151
	v_mul_f32_e32 v84, v84, v161
	v_fmac_f32_e32 v92, v96, v150
	v_fmac_f32_e32 v84, v88, v160
	v_add_f32_e32 v92, v92, v84
	v_and_b32_e32 v150, 0xffff0000, v206
	v_and_b32_e32 v151, 0xffff0000, v210
	v_and_b32_e32 v160, 0xffff0000, v214
	v_and_b32_e32 v161, 0xffff0000, v218
	v_mul_f32_e32 v93, v93, v151
	v_mul_f32_e32 v85, v85, v161
	v_fmac_f32_e32 v93, v97, v150
	v_fmac_f32_e32 v85, v89, v160
	v_add_f32_e32 v93, v93, v85
	v_lshlrev_b32_e32 v150, 16, v207
	v_lshlrev_b32_e32 v151, 16, v211
	v_lshlrev_b32_e32 v160, 16, v215
	v_lshlrev_b32_e32 v161, 16, v219
	v_mul_f32_e32 v94, v94, v151
	v_mul_f32_e32 v86, v86, v161
	v_fmac_f32_e32 v94, v98, v150
	v_fmac_f32_e32 v86, v90, v160
	v_add_f32_e32 v94, v94, v86
	v_and_b32_e32 v150, 0xffff0000, v207
	v_and_b32_e32 v151, 0xffff0000, v211
	v_and_b32_e32 v160, 0xffff0000, v215
	v_and_b32_e32 v161, 0xffff0000, v219
	v_mul_f32_e32 v95, v95, v151
	v_mul_f32_e32 v87, v87, v161
	v_fmac_f32_e32 v95, v99, v150
	v_fmac_f32_e32 v87, v91, v160
	v_add_f32_e32 v95, v95, v87
	v_lshlrev_b32_e32 v150, 16, v208
	v_lshlrev_b32_e32 v151, 16, v212
	v_lshlrev_b32_e32 v160, 16, v216
	v_lshlrev_b32_e32 v161, 16, v220
	v_mul_f32_e32 v76, v76, v151
	v_mul_f32_e32 v68, v68, v161
	v_fmac_f32_e32 v76, v80, v150
	v_fmac_f32_e32 v68, v72, v160
	v_add_f32_e32 v76, v76, v68
	v_and_b32_e32 v150, 0xffff0000, v208
	v_and_b32_e32 v151, 0xffff0000, v212
	v_and_b32_e32 v160, 0xffff0000, v216
	v_and_b32_e32 v161, 0xffff0000, v220
	v_mul_f32_e32 v77, v77, v151
	v_mul_f32_e32 v69, v69, v161
	v_fmac_f32_e32 v77, v81, v150
	v_fmac_f32_e32 v69, v73, v160
	v_add_f32_e32 v77, v77, v69
	v_lshlrev_b32_e32 v150, 16, v209
	v_lshlrev_b32_e32 v151, 16, v213
	v_lshlrev_b32_e32 v160, 16, v217
	v_lshlrev_b32_e32 v161, 16, v221
	v_mul_f32_e32 v78, v78, v151
	v_mul_f32_e32 v70, v70, v161
	v_fmac_f32_e32 v78, v82, v150
	v_fmac_f32_e32 v70, v74, v160
	v_add_f32_e32 v78, v78, v70
	v_and_b32_e32 v150, 0xffff0000, v209
	v_and_b32_e32 v151, 0xffff0000, v213
	v_and_b32_e32 v160, 0xffff0000, v217
	v_and_b32_e32 v161, 0xffff0000, v221
	v_mul_f32_e32 v79, v79, v151
	v_mul_f32_e32 v71, v71, v161
	v_fmac_f32_e32 v79, v83, v150
	v_fmac_f32_e32 v71, v75, v160
	v_add_f32_e32 v79, v79, v71
	v_cvt_pk_bf16_f32 v206, v92, v93
	v_cvt_pk_bf16_f32 v207, v94, v95
	v_cvt_pk_bf16_f32 v208, v76, v77
	v_cvt_pk_bf16_f32 v209, v78, v79
	v_add_u32_e32 v147, 0x10000, v146
	s_nop 0
	global_store_dwordx4 v147, v[206:209], s[74:75]
	v_mul_f32_e32 v64, 0xbfb8aa3b, v64
	v_mul_f32_e32 v65, 0xbfb8aa3b, v65
	v_mul_f32_e32 v66, 0xbfb8aa3b, v66
	v_mul_f32_e32 v67, 0xbfb8aa3b, v67
	v_mul_f32_e32 v60, 0xbfb8aa3b, v60
	v_mul_f32_e32 v61, 0xbfb8aa3b, v61
	v_mul_f32_e32 v62, 0xbfb8aa3b, v62
	v_mul_f32_e32 v63, 0xbfb8aa3b, v63
	v_mul_f32_e32 v56, 0xbfb8aa3b, v56
	v_mul_f32_e32 v57, 0xbfb8aa3b, v57
	v_mul_f32_e32 v58, 0xbfb8aa3b, v58
	v_mul_f32_e32 v59, 0xbfb8aa3b, v59
	v_mul_f32_e32 v52, 0xbfb8aa3b, v52
	v_mul_f32_e32 v53, 0xbfb8aa3b, v53
	v_mul_f32_e32 v54, 0xbfb8aa3b, v54
	v_mul_f32_e32 v55, 0xbfb8aa3b, v55
	v_mul_f32_e32 v48, 0xbfb8aa3b, v48
	v_mul_f32_e32 v49, 0xbfb8aa3b, v49
	v_mul_f32_e32 v50, 0xbfb8aa3b, v50
	v_mul_f32_e32 v51, 0xbfb8aa3b, v51
	v_mul_f32_e32 v44, 0xbfb8aa3b, v44
	v_mul_f32_e32 v45, 0xbfb8aa3b, v45
	v_mul_f32_e32 v46, 0xbfb8aa3b, v46
	v_mul_f32_e32 v47, 0xbfb8aa3b, v47
	v_mul_f32_e32 v40, 0xbfb8aa3b, v40
	v_mul_f32_e32 v41, 0xbfb8aa3b, v41
	v_mul_f32_e32 v42, 0xbfb8aa3b, v42
	v_mul_f32_e32 v43, 0xbfb8aa3b, v43
	v_mul_f32_e32 v36, 0xbfb8aa3b, v36
	v_mul_f32_e32 v37, 0xbfb8aa3b, v37
	v_mul_f32_e32 v38, 0xbfb8aa3b, v38
	v_mul_f32_e32 v39, 0xbfb8aa3b, v39
	v_exp_f32_e32 v64, v64
	v_exp_f32_e32 v65, v65
	v_exp_f32_e32 v66, v66
	v_exp_f32_e32 v67, v67
	v_exp_f32_e32 v60, v60
	v_exp_f32_e32 v61, v61
	v_exp_f32_e32 v62, v62
	v_exp_f32_e32 v63, v63
	v_exp_f32_e32 v56, v56
	v_exp_f32_e32 v57, v57
	v_exp_f32_e32 v58, v58
	v_exp_f32_e32 v59, v59
	v_exp_f32_e32 v52, v52
	v_exp_f32_e32 v53, v53
	v_exp_f32_e32 v54, v54
	v_exp_f32_e32 v55, v55
	v_exp_f32_e32 v48, v48
	v_exp_f32_e32 v49, v49
	v_exp_f32_e32 v50, v50
	v_exp_f32_e32 v51, v51
	v_exp_f32_e32 v44, v44
	v_exp_f32_e32 v45, v45
	v_exp_f32_e32 v46, v46
	v_exp_f32_e32 v47, v47
	v_exp_f32_e32 v40, v40
	v_exp_f32_e32 v41, v41
	v_exp_f32_e32 v42, v42
	v_exp_f32_e32 v43, v43
	v_exp_f32_e32 v36, v36
; __device__ __forceinline__ unsigned cvt_pk_bf16(float lo, float hi) { unsigned r; asm volatile("v_cvt_pk_bf16_f32 %0, %1, %2" : "=v"(r) : "v"(lo), "v"(hi)); return r; }
; __device__ __forceinline__ float sigm_f(float x) { return __builtin_amdgcn_rcpf(1.0f + __expf(-x)); }
; __device__ __forceinline__ float ebflo(unsigned w) { return __uint_as_float(w << 16); }
; __device__ __forceinline__ float ebfhi(unsigned w) { return __uint_as_float(w & 0xffff0000u); }
;     __device__ __forceinline__ void operator()(const f32x4 (&acc)[2][2][4][2], const Unit& u, int wr, int wc, int fr, int fq) const {
;     ...
;             for (int m = 0; m < 4; ++m) { const size_t off = (size_t)(row0 + ai * HALF + m * 16) * 1024 + j0;
;                 const u32x2 t0 = *(const u32x2*)(T0 + off), t1 = *(const u32x2*)(T1 + off), t2 = *(const u32x2*)(T2 + off), t3 = *(const u32x2*)(T3 + off);
;                 const f32x4 g0 = acc[ai][0][m][0], g1 = acc[ai][0][m][1], g2 = acc[ai][1][m][0], g3 = acc[ai][1][m][1];
;                 const float r0 = (sigm_f(g0[0]) * ebflo(t0.x) + sigm_f(g1[0]) * ebflo(t1.x)) + (sigm_f(g2[0]) * ebflo(t2.x) + sigm_f(g3[0]) * ebflo(t3.x));
;                 const float r1 = (sigm_f(g0[1]) * ebfhi(t0.x) + sigm_f(g1[1]) * ebfhi(t1.x)) + (sigm_f(g2[1]) * ebfhi(t2.x) + sigm_f(g3[1]) * ebfhi(t3.x));
;                 const float r2 = (sigm_f(g0[2]) * ebflo(t0.y) + sigm_f(g1[2]) * ebflo(t1.y)) + (sigm_f(g2[2]) * ebflo(t2.y) + sigm_f(g3[2]) * ebflo(t3.y));
;                 const float r3 = (sigm_f(g0[3]) * ebfhi(t0.y) + sigm_f(g1[3]) * ebfhi(t1.y)) + (sigm_f(g2[3]) * ebfhi(t2.y) + sigm_f(g3[3]) * ebfhi(t3.y));
;                 u32x2 w; w.x = cvt_pk_bf16(r0, r1); w.y = cvt_pk_bf16(r2, r3);
;                 *(u32x2*)(MRG + off) = w; }
	v_exp_f32_e32 v37, v37
	v_exp_f32_e32 v38, v38
	v_exp_f32_e32 v39, v39
	v_add_f32_e32 v64, 1.0, v64
	v_add_f32_e32 v65, 1.0, v65
	v_add_f32_e32 v66, 1.0, v66
	v_add_f32_e32 v67, 1.0, v67
	v_add_f32_e32 v60, 1.0, v60
	v_add_f32_e32 v61, 1.0, v61
	v_add_f32_e32 v62, 1.0, v62
	v_add_f32_e32 v63, 1.0, v63
	v_add_f32_e32 v56, 1.0, v56
	v_add_f32_e32 v57, 1.0, v57
	v_add_f32_e32 v58, 1.0, v58
	v_add_f32_e32 v59, 1.0, v59
	v_add_f32_e32 v52, 1.0, v52
	v_add_f32_e32 v53, 1.0, v53
	v_add_f32_e32 v54, 1.0, v54
	v_add_f32_e32 v55, 1.0, v55
	v_add_f32_e32 v48, 1.0, v48
	v_add_f32_e32 v49, 1.0, v49
	v_add_f32_e32 v50, 1.0, v50
	v_add_f32_e32 v51, 1.0, v51
	v_add_f32_e32 v44, 1.0, v44
	v_add_f32_e32 v45, 1.0, v45
	v_add_f32_e32 v46, 1.0, v46
	v_add_f32_e32 v47, 1.0, v47
	v_add_f32_e32 v40, 1.0, v40
	v_add_f32_e32 v41, 1.0, v41
	v_add_f32_e32 v42, 1.0, v42
	v_add_f32_e32 v43, 1.0, v43
	v_add_f32_e32 v36, 1.0, v36
	v_add_f32_e32 v37, 1.0, v37
	v_add_f32_e32 v38, 1.0, v38
	v_add_f32_e32 v39, 1.0, v39
	v_rcp_f32_e32 v64, v64
	v_rcp_f32_e32 v65, v65
	v_rcp_f32_e32 v66, v66
	v_rcp_f32_e32 v67, v67
	v_rcp_f32_e32 v60, v60
	v_rcp_f32_e32 v61, v61
	v_rcp_f32_e32 v62, v62
	v_rcp_f32_e32 v63, v63
	v_rcp_f32_e32 v56, v56
	v_rcp_f32_e32 v57, v57
	v_rcp_f32_e32 v58, v58
	v_rcp_f32_e32 v59, v59
	v_rcp_f32_e32 v52, v52
	v_rcp_f32_e32 v53, v53
	v_rcp_f32_e32 v54, v54
	v_rcp_f32_e32 v55, v55
	v_rcp_f32_e32 v48, v48
	v_rcp_f32_e32 v49, v49
	v_rcp_f32_e32 v50, v50
	v_rcp_f32_e32 v51, v51
	v_rcp_f32_e32 v44, v44
	v_rcp_f32_e32 v45, v45
	v_rcp_f32_e32 v46, v46
	v_rcp_f32_e32 v47, v47
	v_rcp_f32_e32 v40, v40
	v_rcp_f32_e32 v41, v41
	v_rcp_f32_e32 v42, v42
	v_rcp_f32_e32 v43, v43
	v_rcp_f32_e32 v36, v36
	v_rcp_f32_e32 v37, v37
	v_rcp_f32_e32 v38, v38
	v_rcp_f32_e32 v39, v39
	s_nop 1
	v_permlane16_swap_b32_e32 v64, v48
	v_permlane16_swap_b32_e32 v65, v49
	v_permlane16_swap_b32_e32 v66, v50
	v_permlane16_swap_b32_e32 v67, v51
	v_permlane16_swap_b32_e32 v60, v44
	v_permlane16_swap_b32_e32 v61, v45
	v_permlane16_swap_b32_e32 v62, v46
	v_permlane16_swap_b32_e32 v63, v47
	v_permlane16_swap_b32_e32 v56, v40
	v_permlane16_swap_b32_e32 v57, v41
	v_permlane16_swap_b32_e32 v58, v42
	v_permlane16_swap_b32_e32 v59, v43
	v_permlane16_swap_b32_e32 v52, v36
	v_permlane16_swap_b32_e32 v53, v37
	v_permlane16_swap_b32_e32 v54, v38
	v_permlane16_swap_b32_e32 v55, v39
	v_lshlrev_b32_e32 v150, 16, v222
	v_lshlrev_b32_e32 v151, 16, v226
	v_lshlrev_b32_e32 v160, 16, v230
	v_lshlrev_b32_e32 v161, 16, v234
	v_mul_f32_e32 v60, v60, v151
	v_mul_f32_e32 v52, v52, v161
	v_fmac_f32_e32 v60, v64, v150
	v_fmac_f32_e32 v52, v56, v160
	v_add_f32_e32 v60, v60, v52
	v_and_b32_e32 v150, 0xffff0000, v222
	v_and_b32_e32 v151, 0xffff0000, v226
	v_and_b32_e32 v160, 0xffff0000, v230
	v_and_b32_e32 v161, 0xffff0000, v234
	v_mul_f32_e32 v61, v61, v151
	v_mul_f32_e32 v53, v53, v161
	v_fmac_f32_e32 v61, v65, v150
	v_fmac_f32_e32 v53, v57, v160
	v_add_f32_e32 v61, v61, v53
	v_lshlrev_b32_e32 v150, 16, v223
	v_lshlrev_b32_e32 v151, 16, v227
	v_lshlrev_b32_e32 v160, 16, v231
	v_lshlrev_b32_e32 v161, 16, v235
	v_mul_f32_e32 v62, v62, v151
	v_mul_f32_e32 v54, v54, v161
	v_fmac_f32_e32 v62, v66, v150
	v_fmac_f32_e32 v54, v58, v160
	v_add_f32_e32 v62, v62, v54
	v_and_b32_e32 v150, 0xffff0000, v223
	v_and_b32_e32 v151, 0xffff0000, v227
	v_and_b32_e32 v160, 0xffff0000, v231
	v_and_b32_e32 v161, 0xffff0000, v235
	v_mul_f32_e32 v63, v63, v151
	v_mul_f32_e32 v55, v55, v161
	v_fmac_f32_e32 v63, v67, v150
	v_fmac_f32_e32 v55, v59, v160
	v_add_f32_e32 v63, v63, v55
	v_lshlrev_b32_e32 v150, 16, v224
	v_lshlrev_b32_e32 v151, 16, v228
	v_lshlrev_b32_e32 v160, 16, v232
	v_lshlrev_b32_e32 v161, 16, v236
	v_mul_f32_e32 v44, v44, v151
	v_mul_f32_e32 v36, v36, v161
	v_fmac_f32_e32 v44, v48, v150
	v_fmac_f32_e32 v36, v40, v160
	v_add_f32_e32 v44, v44, v36
	v_and_b32_e32 v150, 0xffff0000, v224
	v_and_b32_e32 v151, 0xffff0000, v228
	v_and_b32_e32 v160, 0xffff0000, v232
	v_and_b32_e32 v161, 0xffff0000, v236
	v_mul_f32_e32 v45, v45, v151
	v_mul_f32_e32 v37, v37, v161
	v_fmac_f32_e32 v45, v49, v150
	v_fmac_f32_e32 v37, v41, v160
	v_add_f32_e32 v45, v45, v37
	v_lshlrev_b32_e32 v150, 16, v225
	v_lshlrev_b32_e32 v151, 16, v229
	v_lshlrev_b32_e32 v160, 16, v233
	v_lshlrev_b32_e32 v161, 16, v237
	v_mul_f32_e32 v46, v46, v151
	v_mul_f32_e32 v38, v38, v161
	v_fmac_f32_e32 v46, v50, v150
	v_fmac_f32_e32 v38, v42, v160
	v_add_f32_e32 v46, v46, v38
	v_and_b32_e32 v150, 0xffff0000, v225
	v_and_b32_e32 v151, 0xffff0000, v229
	v_and_b32_e32 v160, 0xffff0000, v233
	v_and_b32_e32 v161, 0xffff0000, v237
	v_mul_f32_e32 v47, v47, v151
	v_mul_f32_e32 v39, v39, v161
	v_fmac_f32_e32 v47, v51, v150
	v_fmac_f32_e32 v39, v43, v160
	v_add_f32_e32 v47, v47, v39
	v_cvt_pk_bf16_f32 v222, v60, v61
	v_cvt_pk_bf16_f32 v223, v62, v63
	v_cvt_pk_bf16_f32 v224, v44, v45
	v_cvt_pk_bf16_f32 v225, v46, v47
	v_add_u32_e32 v147, 0x40000, v146
	s_nop 0
	global_store_dwordx4 v147, v[222:225], s[74:75]
	v_mul_f32_e32 v32, 0xbfb8aa3b, v32
	v_mul_f32_e32 v33, 0xbfb8aa3b, v33
	v_mul_f32_e32 v34, 0xbfb8aa3b, v34
	v_mul_f32_e32 v35, 0xbfb8aa3b, v35
	v_mul_f32_e32 v28, 0xbfb8aa3b, v28
	v_mul_f32_e32 v29, 0xbfb8aa3b, v29
	v_mul_f32_e32 v30, 0xbfb8aa3b, v30
	v_mul_f32_e32 v31, 0xbfb8aa3b, v31
	v_mul_f32_e32 v24, 0xbfb8aa3b, v24
	v_mul_f32_e32 v25, 0xbfb8aa3b, v25
	v_mul_f32_e32 v26, 0xbfb8aa3b, v26
	v_mul_f32_e32 v27, 0xbfb8aa3b, v27
	v_mul_f32_e32 v20, 0xbfb8aa3b, v20
	v_mul_f32_e32 v21, 0xbfb8aa3b, v21
	v_mul_f32_e32 v22, 0xbfb8aa3b, v22
	v_mul_f32_e32 v23, 0xbfb8aa3b, v23
	v_mul_f32_e32 v16, 0xbfb8aa3b, v16
	v_mul_f32_e32 v17, 0xbfb8aa3b, v17
	v_mul_f32_e32 v18, 0xbfb8aa3b, v18
; __device__ __forceinline__ unsigned cvt_pk_bf16(float lo, float hi) { unsigned r; asm volatile("v_cvt_pk_bf16_f32 %0, %1, %2" : "=v"(r) : "v"(lo), "v"(hi)); return r; }
; __device__ __forceinline__ float sigm_f(float x) { return __builtin_amdgcn_rcpf(1.0f + __expf(-x)); }
; __device__ __forceinline__ float ebflo(unsigned w) { return __uint_as_float(w << 16); }
; __device__ __forceinline__ float ebfhi(unsigned w) { return __uint_as_float(w & 0xffff0000u); }
;     __device__ __forceinline__ void operator()(const f32x4 (&acc)[2][2][4][2], const Unit& u, int wr, int wc, int fr, int fq) const {
;     ...
;             for (int m = 0; m < 4; ++m) { const size_t off = (size_t)(row0 + ai * HALF + m * 16) * 1024 + j0;
;                 const u32x2 t0 = *(const u32x2*)(T0 + off), t1 = *(const u32x2*)(T1 + off), t2 = *(const u32x2*)(T2 + off), t3 = *(const u32x2*)(T3 + off);
;                 const f32x4 g0 = acc[ai][0][m][0], g1 = acc[ai][0][m][1], g2 = acc[ai][1][m][0], g3 = acc[ai][1][m][1];
;                 const float r0 = (sigm_f(g0[0]) * ebflo(t0.x) + sigm_f(g1[0]) * ebflo(t1.x)) + (sigm_f(g2[0]) * ebflo(t2.x) + sigm_f(g3[0]) * ebflo(t3.x));
;                 const float r1 = (sigm_f(g0[1]) * ebfhi(t0.x) + sigm_f(g1[1]) * ebfhi(t1.x)) + (sigm_f(g2[1]) * ebfhi(t2.x) + sigm_f(g3[1]) * ebfhi(t3.x));
;                 const float r2 = (sigm_f(g0[2]) * ebflo(t0.y) + sigm_f(g1[2]) * ebflo(t1.y)) + (sigm_f(g2[2]) * ebflo(t2.y) + sigm_f(g3[2]) * ebflo(t3.y));
;                 const float r3 = (sigm_f(g0[3]) * ebfhi(t0.y) + sigm_f(g1[3]) * ebfhi(t1.y)) + (sigm_f(g2[3]) * ebfhi(t2.y) + sigm_f(g3[3]) * ebfhi(t3.y));
;                 u32x2 w; w.x = cvt_pk_bf16(r0, r1); w.y = cvt_pk_bf16(r2, r3);
;                 *(u32x2*)(MRG + off) = w; }
	v_mul_f32_e32 v19, 0xbfb8aa3b, v19
	v_mul_f32_e32 v12, 0xbfb8aa3b, v12
	v_mul_f32_e32 v13, 0xbfb8aa3b, v13
	v_mul_f32_e32 v14, 0xbfb8aa3b, v14
	v_mul_f32_e32 v15, 0xbfb8aa3b, v15
	v_mul_f32_e32 v8, 0xbfb8aa3b, v8
	v_mul_f32_e32 v9, 0xbfb8aa3b, v9
	v_mul_f32_e32 v10, 0xbfb8aa3b, v10
	v_mul_f32_e32 v11, 0xbfb8aa3b, v11
	v_mul_f32_e32 v4, 0xbfb8aa3b, v4
	v_mul_f32_e32 v5, 0xbfb8aa3b, v5
	v_mul_f32_e32 v6, 0xbfb8aa3b, v6
	v_mul_f32_e32 v7, 0xbfb8aa3b, v7
	v_exp_f32_e32 v32, v32
	v_exp_f32_e32 v33, v33
	v_exp_f32_e32 v34, v34
	v_exp_f32_e32 v35, v35
	v_exp_f32_e32 v28, v28
	v_exp_f32_e32 v29, v29
	v_exp_f32_e32 v30, v30
	v_exp_f32_e32 v31, v31
	v_exp_f32_e32 v24, v24
	v_exp_f32_e32 v25, v25
	v_exp_f32_e32 v26, v26
	v_exp_f32_e32 v27, v27
	v_exp_f32_e32 v20, v20
	v_exp_f32_e32 v21, v21
	v_exp_f32_e32 v22, v22
	v_exp_f32_e32 v23, v23
	v_exp_f32_e32 v16, v16
	v_exp_f32_e32 v17, v17
	v_exp_f32_e32 v18, v18
	v_exp_f32_e32 v19, v19
	v_exp_f32_e32 v12, v12
	v_exp_f32_e32 v13, v13
	v_exp_f32_e32 v14, v14
	v_exp_f32_e32 v15, v15
	v_exp_f32_e32 v8, v8
	v_exp_f32_e32 v9, v9
	v_exp_f32_e32 v10, v10
	v_exp_f32_e32 v11, v11
	v_exp_f32_e32 v4, v4
	v_exp_f32_e32 v5, v5
	v_exp_f32_e32 v6, v6
	v_exp_f32_e32 v7, v7
	v_add_f32_e32 v32, 1.0, v32
	v_add_f32_e32 v33, 1.0, v33
	v_add_f32_e32 v34, 1.0, v34
	v_add_f32_e32 v35, 1.0, v35
	v_add_f32_e32 v28, 1.0, v28
	v_add_f32_e32 v29, 1.0, v29
	v_add_f32_e32 v30, 1.0, v30
	v_add_f32_e32 v31, 1.0, v31
	v_add_f32_e32 v24, 1.0, v24
	v_add_f32_e32 v25, 1.0, v25
	v_add_f32_e32 v26, 1.0, v26
	v_add_f32_e32 v27, 1.0, v27
	v_add_f32_e32 v20, 1.0, v20
	v_add_f32_e32 v21, 1.0, v21
	v_add_f32_e32 v22, 1.0, v22
	v_add_f32_e32 v23, 1.0, v23
	v_add_f32_e32 v16, 1.0, v16
	v_add_f32_e32 v17, 1.0, v17
	v_add_f32_e32 v18, 1.0, v18
	v_add_f32_e32 v19, 1.0, v19
	v_add_f32_e32 v12, 1.0, v12
	v_add_f32_e32 v13, 1.0, v13
	v_add_f32_e32 v14, 1.0, v14
	v_add_f32_e32 v15, 1.0, v15
	v_add_f32_e32 v8, 1.0, v8
	v_add_f32_e32 v9, 1.0, v9
	v_add_f32_e32 v10, 1.0, v10
	v_add_f32_e32 v11, 1.0, v11
	v_add_f32_e32 v4, 1.0, v4
	v_add_f32_e32 v5, 1.0, v5
	v_add_f32_e32 v6, 1.0, v6
	v_add_f32_e32 v7, 1.0, v7
	v_rcp_f32_e32 v32, v32
	v_rcp_f32_e32 v33, v33
	v_rcp_f32_e32 v34, v34
	v_rcp_f32_e32 v35, v35
	v_rcp_f32_e32 v28, v28
	v_rcp_f32_e32 v29, v29
	v_rcp_f32_e32 v30, v30
	v_rcp_f32_e32 v31, v31
	v_rcp_f32_e32 v24, v24
	v_rcp_f32_e32 v25, v25
	v_rcp_f32_e32 v26, v26
	v_rcp_f32_e32 v27, v27
	v_rcp_f32_e32 v20, v20
	v_rcp_f32_e32 v21, v21
	v_rcp_f32_e32 v22, v22
	v_rcp_f32_e32 v23, v23
	v_rcp_f32_e32 v16, v16
	v_rcp_f32_e32 v17, v17
	v_rcp_f32_e32 v18, v18
	v_rcp_f32_e32 v19, v19
	v_rcp_f32_e32 v12, v12
	v_rcp_f32_e32 v13, v13
	v_rcp_f32_e32 v14, v14
	v_rcp_f32_e32 v15, v15
	v_rcp_f32_e32 v8, v8
	v_rcp_f32_e32 v9, v9
	v_rcp_f32_e32 v10, v10
	v_rcp_f32_e32 v11, v11
	v_rcp_f32_e32 v4, v4
	v_rcp_f32_e32 v5, v5
	v_rcp_f32_e32 v6, v6
	v_rcp_f32_e32 v7, v7
	s_nop 1
	v_permlane16_swap_b32_e32 v32, v16
	v_permlane16_swap_b32_e32 v33, v17
	v_permlane16_swap_b32_e32 v34, v18
	v_permlane16_swap_b32_e32 v35, v19
	v_permlane16_swap_b32_e32 v28, v12
	v_permlane16_swap_b32_e32 v29, v13
	v_permlane16_swap_b32_e32 v30, v14
	v_permlane16_swap_b32_e32 v31, v15
	v_permlane16_swap_b32_e32 v24, v8
	v_permlane16_swap_b32_e32 v25, v9
	v_permlane16_swap_b32_e32 v26, v10
	v_permlane16_swap_b32_e32 v27, v11
	v_permlane16_swap_b32_e32 v20, v4
	v_permlane16_swap_b32_e32 v21, v5
	v_permlane16_swap_b32_e32 v22, v6
	v_permlane16_swap_b32_e32 v23, v7
	v_lshlrev_b32_e32 v150, 16, v238
	v_lshlrev_b32_e32 v151, 16, v242
	v_lshlrev_b32_e32 v160, 16, v152
	v_lshlrev_b32_e32 v161, 16, v156
	v_mul_f32_e32 v28, v28, v151
	v_mul_f32_e32 v20, v20, v161
	v_fmac_f32_e32 v28, v32, v150
	v_fmac_f32_e32 v20, v24, v160
	v_add_f32_e32 v28, v28, v20
	v_and_b32_e32 v150, 0xffff0000, v238
	v_and_b32_e32 v151, 0xffff0000, v242
	v_and_b32_e32 v160, 0xffff0000, v152
	v_and_b32_e32 v161, 0xffff0000, v156
	v_mul_f32_e32 v29, v29, v151
	v_mul_f32_e32 v21, v21, v161
	v_fmac_f32_e32 v29, v33, v150
	v_fmac_f32_e32 v21, v25, v160
	v_add_f32_e32 v29, v29, v21
	v_lshlrev_b32_e32 v150, 16, v239
	v_lshlrev_b32_e32 v151, 16, v243
	v_lshlrev_b32_e32 v160, 16, v153
	v_lshlrev_b32_e32 v161, 16, v157
	v_mul_f32_e32 v30, v30, v151
	v_mul_f32_e32 v22, v22, v161
	v_fmac_f32_e32 v30, v34, v150
	v_fmac_f32_e32 v22, v26, v160
	v_add_f32_e32 v30, v30, v22
	v_and_b32_e32 v150, 0xffff0000, v239
	v_and_b32_e32 v151, 0xffff0000, v243
	v_and_b32_e32 v160, 0xffff0000, v153
	v_and_b32_e32 v161, 0xffff0000, v157
	v_mul_f32_e32 v31, v31, v151
	v_mul_f32_e32 v23, v23, v161
	v_fmac_f32_e32 v31, v35, v150
	v_fmac_f32_e32 v23, v27, v160
	v_add_f32_e32 v31, v31, v23
	v_lshlrev_b32_e32 v150, 16, v240
	v_lshlrev_b32_e32 v151, 16, v244
	v_lshlrev_b32_e32 v160, 16, v154
	v_lshlrev_b32_e32 v161, 16, v158
	v_mul_f32_e32 v12, v12, v151
	v_mul_f32_e32 v4, v4, v161
	v_fmac_f32_e32 v12, v16, v150
	v_fmac_f32_e32 v4, v8, v160
	v_add_f32_e32 v12, v12, v4
	v_and_b32_e32 v150, 0xffff0000, v240
	v_and_b32_e32 v151, 0xffff0000, v244
	v_and_b32_e32 v160, 0xffff0000, v154
	v_and_b32_e32 v161, 0xffff0000, v158
	v_mul_f32_e32 v13, v13, v151
	v_mul_f32_e32 v5, v5, v161
	v_fmac_f32_e32 v13, v17, v150
	v_fmac_f32_e32 v5, v9, v160
	v_add_f32_e32 v13, v13, v5
	v_lshlrev_b32_e32 v150, 16, v241
	v_lshlrev_b32_e32 v151, 16, v245
	v_lshlrev_b32_e32 v160, 16, v155
	v_lshlrev_b32_e32 v161, 16, v159
	v_mul_f32_e32 v14, v14, v151
	v_mul_f32_e32 v6, v6, v161
	v_fmac_f32_e32 v14, v18, v150
	v_fmac_f32_e32 v6, v10, v160
	v_add_f32_e32 v14, v14, v6
	v_and_b32_e32 v150, 0xffff0000, v241
	v_and_b32_e32 v151, 0xffff0000, v245
	v_and_b32_e32 v160, 0xffff0000, v155
	v_and_b32_e32 v161, 0xffff0000, v159
	v_mul_f32_e32 v15, v15, v151
	v_mul_f32_e32 v7, v7, v161
	v_fmac_f32_e32 v15, v19, v150
	v_fmac_f32_e32 v7, v11, v160
	v_add_f32_e32 v15, v15, v7
	v_cvt_pk_bf16_f32 v238, v28, v29
	v_cvt_pk_bf16_f32 v239, v30, v31
	v_cvt_pk_bf16_f32 v240, v12, v13
	v_cvt_pk_bf16_f32 v241, v14, v15
	v_add_u32_e32 v147, 0x50000, v146
	s_nop 0
	global_store_dwordx4 v147, v[238:241], s[74:75]
